# P2: workgroups with only 14 tiles (bid>=112) start ~half a tile later (desynchronised epilogue store bursts)
# speedup vs baseline: 1.0133x; 1.0133x over previous
;     __device__ bool next(int i, Unit& u) const { if (i >= 2) return false; const int x = c & 7, j = c >> 3; u.pm = 64 * i + 8 * x + (j >> 2); u.pn = j & 3; u.ao = 0; u.bo = 0; u.ks = 0; return true; }
;     __device__ bool next(int i, Unit& u) const { if (i >= 1 || c >= 64) return false; u.pm = 128 + (c & 3); u.pn = (c >> 2) & 3; u.ks = c >> 4; u.ao = u.ks * 512; u.bo = u.ks * 512; return true; }
;     __device__ bool next(int i, Unit& u) const {
;         const long L = (long)i * G + c; if (L >= nwg) return false;
;         int wgid = (int)L; { const int q = nwg / NXCD, r = nwg % NXCD, xcd = wgid % NXCD, off = wgid / NXCD; wgid = (xcd < r ? xcd * (q + 1) : r * (q + 1) + (xcd - r) * q) + off; }
;         const int nig = WGM * nN, gid = wgid / nig, fm = gid * WGM, gsz = (nM - fm) < WGM ? (nM - fm) : WGM;
;         u.pm = fm + ((wgid % nig) % gsz); u.pn = (wgid % nig) / gsz; u.ao = u.pn * acol; u.bo = 0; u.ks = 0; return true;
; __global__ void __launch_bounds__(512, 2) fwd_megakernel(Args a) {
;     ...
;         pg8::Gemm g{(const bf16_t*)a.out, (const bf16_t*)(a.ws + WS_WIN), MT, LDU, 1024, 1024, 1024, 0};
;         pg8::StaticOrder S; S.init(MT, LDU, G, bid);
;         pg8::EpiBf16 E{U, LDU, 8, 16, 4, 8};
;         pg8::gemm_phase<pg8::EpiBf16, pg8::StaticOrder, true, true>(L, g, S, E);
.LBB0_175:
	s_or_b64 exec, exec, s[0:1]
	s_waitcnt vmcnt(1)
	v_mov_b32_e32 v8, v180
	s_cmpk_lt_i32 s2, 0xe70
	s_waitcnt lgkmcnt(0)
	s_barrier
	s_cselect_b64 s[0:1], -1, 0
	s_cmpk_lt_i32 s2, 0x70
	s_cbranch_scc1 .Lp2_nostagger
	s_sleep 127
	s_sleep 127
	s_sleep 127
.Lp2_nostagger:
	s_cmpk_gt_i32 s2, 0xe6f
	v_readfirstlane_b32 s12, v8
	s_cbranch_scc1 .LBB0_177
	s_and_b32 s4, s2, 7
	s_lshr_b32 s5, s2, 3
	s_cmpk_lt_u32 s5, 0x18c
	s_cbranch_scc0 .Lxpl1_xp
	s_mul_i32 s4, s4, 0x18c
	s_add_i32 s4, s4, s5
	s_lshr_b32 s6, s4, 6
	s_mul_i32 s6, s6, 0xaaab
	s_lshr_b32 s6, s6, 17
	s_mul_i32 s7, s6, 0xc0
	s_sub_i32 s8, s4, s7
	s_mov_b32 s10, 4
	s_branch .Lxpl1_common
